# attention merge and pooled A2 stores write-back instead of sc1 (no write-through ack in the per-iteration vmcnt(0) waits)
# speedup vs baseline: 1.0078x; 1.0078x over previous
; __device__ __forceinline__ unsigned pk2(float lo, float hi) { return f2bf(lo) | (f2bf(hi) << 16); }
; __global__ void __launch_bounds__(NTHREADS, 2) mega_fwd(Args args) {
;     ...
; #pragma unroll 4
;                     for (int it = tid; it < 256 * 16; it += NTHREADS) {
;                         const int pr = it >> 4, pos = s0 + pr, c8 = it & 15;
;                         const u32x4 b0 = *(const u32x4*)(Opart + ((size_t)0 * S + pos) * 1024 + h * 128 + 8 * c8);
;                         const u32x4 b1 = *(const u32x4*)(Opart + ((size_t)1 * S + pos) * 1024 + h * 128 + 8 * c8);
;                         const u32x4 b2 = *(const u32x4*)(Opart + ((size_t)2 * S + pos) * 1024 + h * 128 + 8 * c8);
;                         const f32x4 w = mw[pr];
;                         u32x4 pk;
; #pragma unroll
;                         for (int e = 0; e < 4; ++e) {
;                             const float lo = __uint_as_float(b0[e] << 16) * w[0] + __uint_as_float(b1[e] << 16) * w[1] + __uint_as_float(b2[e] << 16) * w[2];
;                             const float hi = __uint_as_float(b0[e] & 0xffff0000u) * w[0] + __uint_as_float(b1[e] & 0xffff0000u) * w[1] + __uint_as_float(b2[e] & 0xffff0000u) * w[2];
;                             pk[e] = pk2(lo, hi); }
;                         asm volatile("global_store_dwordx4 %0, %1, off sc1\n\ts_nop 1" :: "v"(A2 + (size_t)pos * D + 1024 + h * 128 + 8 * c8), "v"(pk) : "memory");
;                     }
.LBB0_598:
	v_ashrrev_i32_e32 v2, 4, v1
	v_add_u32_e32 v18, s13, v2
	v_ashrrev_i32_e32 v19, 31, v18
	v_lshlrev_b64 v[2:3], 11, v[18:19]
	v_lshl_add_u64 v[2:3], s[72:73], 0, v[2:3]
	v_and_b32_e32 v4, 0x78, v0
	v_lshl_add_u64 v[2:3], v[2:3], 0, s[76:77]
	v_lshlrev_b32_e32 v96, 1, v4
	v_lshl_add_u64 v[10:11], v[2:3], 0, v[96:97]
	s_mov_b32 s8, 0x1000000
	v_add_co_u32_e32 v6, vcc, s8, v10
	s_brev_b32 s8, 64
	s_nop 0
	v_addc_co_u32_e32 v7, vcc, 0, v11, vcc
	flat_load_dwordx4 v[2:5], v[10:11]
	v_and_b32_e32 v14, -16, v1
	flat_load_dwordx4 v[6:9], v[6:7]
	v_add_co_u32_e32 v10, vcc, s8, v10
	v_add_u32_e32 v14, 0, v14
	s_nop 0
	v_addc_co_u32_e32 v11, vcc, 0, v11, vcc
	flat_load_dwordx4 v[10:13], v[10:11]
	ds_read_b96 v[14:16], v14
	s_mov_b64 s[40:41], 0x800
	s_movk_i32 s8, 0xdff
	v_cmp_lt_i32_e32 vcc, s8, v1
	v_add_u32_e32 v0, 0x1000, v0
	s_or_b64 s[60:61], vcc, s[60:61]
	s_waitcnt vmcnt(0) lgkmcnt(0)
	v_lshlrev_b32_e32 v22, 16, v2
	v_lshlrev_b32_e32 v21, 16, v3
	v_lshlrev_b32_e32 v23, 16, v7
	v_lshlrev_b32_e32 v20, 16, v6
	v_pk_mul_f32 v[22:23], v[14:15], v[22:23]
	v_and_b32_e32 v2, 0xffff0000, v2
	v_pk_fma_f32 v[20:21], v[14:15], v[20:21], v[22:23] op_sel:[1,0,0] op_sel_hi:[0,1,1]
	v_lshlrev_b32_e32 v23, 16, v11
	v_lshlrev_b32_e32 v22, 16, v10
	v_pk_fma_f32 v[20:21], v[16:17], v[22:23], v[20:21] op_sel_hi:[0,1,1]
	v_and_b32_e32 v23, 0xffff0000, v3
	v_and_b32_e32 v3, 0xffff0000, v7
	v_and_b32_e32 v22, 0xffff0000, v6
	v_pk_mul_f32 v[2:3], v[14:15], v[2:3]
	v_and_b32_e32 v7, 0xffff0000, v11
	v_pk_fma_f32 v[2:3], v[14:15], v[22:23], v[2:3] op_sel:[1,0,0] op_sel_hi:[0,1,1]
	v_and_b32_e32 v6, 0xffff0000, v10
	v_lshlrev_b32_e32 v11, 16, v9
	v_lshlrev_b32_e32 v10, 16, v4
	v_pk_fma_f32 v[2:3], v[16:17], v[6:7], v[2:3] op_sel_hi:[0,1,1]
	v_lshlrev_b32_e32 v6, 16, v8
	v_lshlrev_b32_e32 v7, 16, v5
	v_pk_mul_f32 v[10:11], v[14:15], v[10:11]
	v_and_b32_e32 v4, 0xffff0000, v4
	v_pk_fma_f32 v[6:7], v[14:15], v[6:7], v[10:11] op_sel:[1,0,0] op_sel_hi:[0,1,1]
	v_lshlrev_b32_e32 v11, 16, v13
	v_lshlrev_b32_e32 v10, 16, v12
	v_pk_fma_f32 v[6:7], v[16:17], v[10:11], v[6:7] op_sel_hi:[0,1,1]
	v_and_b32_e32 v11, 0xffff0000, v5
	v_and_b32_e32 v5, 0xffff0000, v9
	v_and_b32_e32 v10, 0xffff0000, v8
	v_pk_mul_f32 v[4:5], v[14:15], v[4:5]
	v_and_b32_e32 v9, 0xffff0000, v13
	v_pk_fma_f32 v[4:5], v[14:15], v[10:11], v[4:5] op_sel:[1,0,0] op_sel_hi:[0,1,1]
	v_and_b32_e32 v8, 0xffff0000, v12
	v_bfe_u32 v10, v3, 16, 1
	v_bfe_u32 v11, v2, 16, 1
	v_pk_fma_f32 v[4:5], v[16:17], v[8:9], v[4:5] op_sel_hi:[0,1,1]
	v_add3_u32 v2, v2, v11, s5
	v_add3_u32 v3, v3, v10, s5
	v_bfe_u32 v10, v6, 16, 1
	v_bfe_u32 v11, v7, 16, 1
	v_bfe_u32 v8, v5, 16, 1
	v_bfe_u32 v9, v4, 16, 1
	v_add3_u32 v7, v7, v11, s5
	v_add3_u32 v6, v6, v10, s5
	v_add3_u32 v4, v4, v9, s5
	v_add3_u32 v5, v5, v8, s5
	v_lshrrev_b32_e32 v6, 16, v6
	v_lshrrev_b32_e32 v7, 16, v7
	v_bfe_u32 v8, v20, 16, 1
	v_bfe_u32 v9, v21, 16, 1
	v_and_or_b32 v5, v5, s62, v7
	v_and_or_b32 v4, v4, s62, v6
	v_lshlrev_b64 v[6:7], 12, v[18:19]
	v_add3_u32 v9, v21, v9, s5
	v_add3_u32 v8, v20, v8, s5
	v_lshl_add_u64 v[6:7], s[30:31], 0, v[6:7]
	v_lshrrev_b32_e32 v8, 16, v8
	v_lshrrev_b32_e32 v9, 16, v9
	v_lshl_add_u64 v[6:7], v[6:7], 0, v[96:97]
	v_and_or_b32 v3, v3, s62, v9
	v_and_or_b32 v2, v2, s62, v8
	v_lshl_add_u64 v[6:7], v[6:7], 0, s[40:41]
	global_store_dwordx4 v[6:7], v[2:5], off
	s_nop 1
	v_add_u32_e32 v2, 0x200, v1
	v_mov_b32_e32 v1, v2
	s_andn2_b64 exec, exec, s[60:61]
	s_cbranch_execnz .LBB0_598
	s_branch .LBB0_503

; template <int HW> __device__ __forceinline__ void pooled_item(const bf16* __restrict__ ub, bf16* __restrict__ pb, int s) {
;     u32x4 v[2 * HW];
; #pragma unroll
;     for (int j = 0; j < 2 * HW; ++j) { int t = s - HW + j; t = t < 0 ? 0 : (t > S - 1 ? S - 1 : t); v[j] = *(const u32x4*)(ub + (size_t)t * 1024); }
; __global__ void __launch_bounds__(NTHREADS, 2) mega_fwd(Args args) {
;     ...
;             for (int it = gt; it < S * 128; it += ngt) {
;                 const int g = it / (S * 32), rem = it - g * (S * 32), s = rem >> 5, ch = g * 32 + (rem & 31);
;                 const bf16* ub = Ub + ch * 8;
;                 if (g == 0) pooled_item<1>(ub, PB + ch * 8, s);
;                 else if (g == 1) pooled_item<2>(ub, PB + ch * 8, s);
;                 else if (g == 2) pooled_item<4>(ub, PB + ch * 8, s);
;                 else pooled_item<8>(ub, PB + ch * 8, s);
;             }
.LBB0_602:
	v_ashrrev_i32_e32 v0, 31, v45
	v_lshrrev_b32_e32 v0, 14, v0
	v_add_u32_e32 v0, v45, v0
	v_ashrrev_i32_e32 v1, 18, v0
	v_and_b32_e32 v0, 0xfffc0000, v0
	v_sub_u32_e32 v0, v45, v0
	v_ashrrev_i32_e32 v36, 5, v0
	v_and_b32_e32 v0, 0xf8, v49
	v_lshl_or_b32 v0, v1, 8, v0
	v_ashrrev_i32_e32 v1, 31, v0
	v_add_u32_e32 v2, 0x3ffff, v45
	s_mov_b32 s8, 0x7fffe
	v_lshl_add_u64 v[40:41], v[0:1], 1, s[2:3]
	v_cmp_lt_u32_e32 vcc, s8, v2
	s_and_saveexec_b64 s[8:9], vcc
	s_xor_b64 s[16:17], exec, s[8:9]
	s_cbranch_execz .LBB0_614
	v_and_b32_e32 v2, 0xfffc0000, v45
	s_mov_b32 s8, 0x7ffff
	v_lshl_add_u64 v[38:39], v[0:1], 1, s[66:67]
	v_cmp_lt_i32_e32 vcc, s8, v2
	s_mov_b64 s[18:19], 0
	s_mov_b64 s[28:29], 0
	s_and_saveexec_b64 s[8:9], vcc
	s_xor_b64 s[26:27], exec, s[8:9]
	s_cbranch_execz .LBB0_607
	s_mov_b32 s8, 0x80000
	v_cmp_eq_u32_e32 vcc, s8, v2
	s_mov_b64 s[30:31], -1
	s_and_saveexec_b64 s[28:29], vcc
	s_cbranch_execz .LBB0_606
	v_add_u32_e32 v32, -4, v36
	v_med3_i32 v0, v32, 0, v225
	v_lshlrev_b32_e32 v96, 11, v0
	v_lshl_add_u64 v[0:1], v[40:41], 0, v[96:97]
	v_add_u32_e32 v33, -3, v36
	flat_load_dwordx4 v[28:31], v[0:1]
	v_med3_i32 v0, v33, 0, v225
	v_lshlrev_b32_e32 v96, 11, v0
	v_lshl_add_u64 v[0:1], v[40:41], 0, v[96:97]
	v_add_u32_e32 v34, -2, v36
	flat_load_dwordx4 v[24:27], v[0:1]
	v_med3_i32 v0, v34, 0, v225
	v_lshlrev_b32_e32 v96, 11, v0
	v_lshl_add_u64 v[0:1], v[40:41], 0, v[96:97]
	v_add_u32_e32 v35, -1, v36
	flat_load_dwordx4 v[8:11], v[0:1]
	v_med3_i32 v0, v35, 0, v225
	v_lshlrev_b32_e32 v96, 11, v0
	v_lshl_add_u64 v[0:1], v[40:41], 0, v[96:97]
	flat_load_dwordx4 v[12:15], v[0:1]
	v_med3_i32 v0, v36, 0, v225
	v_add_u32_e32 v37, 1, v36
	v_lshlrev_b32_e32 v96, 11, v0
	v_med3_i32 v4, v37, 0, v225
	v_lshl_add_u64 v[0:1], v[40:41], 0, v[96:97]
	v_lshlrev_b32_e32 v96, 11, v4
	v_lshl_add_u64 v[4:5], v[40:41], 0, v[96:97]
	v_add_u32_e32 v43, 2, v36
	flat_load_dwordx4 v[0:3], v[0:1]
	v_add_u32_e32 v47, 3, v36
	flat_load_dwordx4 v[20:23], v[4:5]
	v_med3_i32 v4, v43, 0, v225
	v_lshlrev_b32_e32 v96, 11, v4
	v_lshl_add_u64 v[4:5], v[40:41], 0, v[96:97]
	flat_load_dwordx4 v[16:19], v[4:5]
	v_med3_i32 v4, v47, 0, v225
	v_lshlrev_b32_e32 v96, 11, v4
	v_lshl_add_u64 v[4:5], v[40:41], 0, v[96:97]
	flat_load_dwordx4 v[4:7], v[4:5]
	v_cmp_gt_u32_e32 vcc, s33, v32
	s_xor_b64 s[30:31], exec, -1
	s_waitcnt vmcnt(0) lgkmcnt(0)
; __device__ __forceinline__ unsigned pk2(float lo, float hi) { return f2bf(lo) | (f2bf(hi) << 16); }
; template <int HW> __device__ __forceinline__ void pooled_item(const bf16* __restrict__ ub, bf16* __restrict__ pb, int s) {
;     ...
;     float a[8];
; #pragma unroll
;     for (int e = 0; e < 8; ++e) a[e] = 0.f;
; #pragma unroll
;     for (int j = 0; j < 2 * HW; ++j) { const int t = s - HW + j; const float mk = (t >= 0 && t < S) ? 1.f : 0.f;
; #pragma unroll
;         for (int e = 0; e < 4; ++e) { a[2 * e] += mk * __uint_as_float(v[j][e] << 16); a[2 * e + 1] += mk * __uint_as_float(v[j][e] & 0xffff0000u); } }
;     const int lo = (s - HW) < 0 ? 0 : (s - HW), hi = (s + HW) > S ? S : (s + HW);
;     const float ic = 1.0f / (float)(hi - lo);
;     const u32x4 c = v[HW];
;     u32x4 ov;
; #pragma unroll
;     for (int e = 0; e < 4; ++e) ov[e] = pk2(a[2 * e] * ic - __uint_as_float(c[e] << 16), a[2 * e + 1] * ic - __uint_as_float(c[e] & 0xffff0000u));
;     asm volatile("global_store_dwordx4 %0, %1, off sc1\n\ts_nop 1" :: "v"(pb + (size_t)s * D), "v"(ov) : "memory");
	v_lshlrev_b32_e32 v32, 16, v28
	v_cndmask_b32_e64 v46, 0, 1.0, vcc
	v_cmp_gt_u32_e32 vcc, s33, v33
	v_lshlrev_b32_e32 v33, 16, v29
	v_and_b32_e32 v29, 0xffff0000, v29
	v_and_b32_e32 v28, 0xffff0000, v28
	v_cndmask_b32_e64 v44, 0, 1.0, vcc
	v_cmp_gt_u32_e32 vcc, s33, v34
	v_pk_fma_f32 v[32:33], v[46:47], v[32:33], 0 op_sel_hi:[0,1,0]
	v_lshlrev_b32_e32 v51, 16, v25
	v_lshlrev_b32_e32 v50, 16, v24
	v_pk_fma_f32 v[28:29], v[46:47], v[28:29], 0 op_sel_hi:[0,1,0]
	v_and_b32_e32 v25, 0xffff0000, v25
	v_and_b32_e32 v24, 0xffff0000, v24
	v_cndmask_b32_e64 v34, 0, 1.0, vcc
	v_cmp_gt_u32_e32 vcc, s33, v35
	v_pk_fma_f32 v[32:33], v[44:45], v[50:51], v[32:33] op_sel_hi:[0,1,1]
	v_lshlrev_b32_e32 v51, 16, v9
	v_lshlrev_b32_e32 v50, 16, v8
	v_pk_fma_f32 v[24:25], v[44:45], v[24:25], v[28:29] op_sel_hi:[0,1,1]
	v_and_b32_e32 v9, 0xffff0000, v9
	v_and_b32_e32 v8, 0xffff0000, v8
	v_cndmask_b32_e64 v42, 0, 1.0, vcc
	v_pk_fma_f32 v[32:33], v[34:35], v[50:51], v[32:33] op_sel_hi:[0,1,1]
	v_lshlrev_b32_e32 v51, 16, v13
	v_lshlrev_b32_e32 v50, 16, v12
	v_pk_fma_f32 v[8:9], v[34:35], v[8:9], v[24:25] op_sel_hi:[0,1,1]
	v_and_b32_e32 v13, 0xffff0000, v13
	v_and_b32_e32 v12, 0xffff0000, v12
	v_pk_fma_f32 v[8:9], v[42:43], v[12:13], v[8:9] op_sel_hi:[0,1,1]
	v_lshlrev_b32_e32 v13, 16, v31
	v_lshlrev_b32_e32 v12, 16, v30
	v_pk_fma_f32 v[12:13], v[46:47], v[12:13], 0 op_sel_hi:[0,1,0]
	v_lshlrev_b32_e32 v25, 16, v27
	v_lshlrev_b32_e32 v24, 16, v26
	v_pk_fma_f32 v[12:13], v[44:45], v[24:25], v[12:13] op_sel_hi:[0,1,1]
	v_lshlrev_b32_e32 v25, 16, v11
	v_lshlrev_b32_e32 v24, 16, v10
	v_pk_fma_f32 v[12:13], v[34:35], v[24:25], v[12:13] op_sel_hi:[0,1,1]
	v_lshlrev_b32_e32 v25, 16, v15
	v_lshlrev_b32_e32 v24, 16, v14
	v_pk_fma_f32 v[12:13], v[42:43], v[24:25], v[12:13] op_sel_hi:[0,1,1]
	v_and_b32_e32 v25, 0xffff0000, v31
	v_and_b32_e32 v24, 0xffff0000, v30
	v_pk_fma_f32 v[24:25], v[46:47], v[24:25], 0 op_sel_hi:[0,1,0]
	v_and_b32_e32 v27, 0xffff0000, v27
	v_and_b32_e32 v26, 0xffff0000, v26
	v_pk_fma_f32 v[24:25], v[44:45], v[26:27], v[24:25] op_sel_hi:[0,1,1]
	v_and_b32_e32 v11, 0xffff0000, v11
	v_and_b32_e32 v10, 0xffff0000, v10
	v_pk_fma_f32 v[10:11], v[34:35], v[10:11], v[24:25] op_sel_hi:[0,1,1]
	v_and_b32_e32 v15, 0xffff0000, v15
	v_and_b32_e32 v14, 0xffff0000, v14
	v_pk_fma_f32 v[10:11], v[42:43], v[14:15], v[10:11] op_sel_hi:[0,1,1]
	v_max_i32_e32 v15, 4, v36
	v_min_i32_e32 v25, 0x1ffc, v36
	v_sub_u32_e32 v15, v25, v15
	v_add_u32_e32 v15, 8, v15
	v_cvt_f32_i32_e32 v15, v15
	v_cmp_gt_u32_e32 vcc, s33, v36
	v_pk_fma_f32 v[32:33], v[42:43], v[50:51], v[32:33] op_sel_hi:[0,1,1]
	v_lshlrev_b32_e32 v51, 16, v1
	v_div_scale_f32 v25, s[8:9], v15, v15, 1.0
	v_rcp_f32_e32 v31, v25
	v_cndmask_b32_e64 v14, 0, 1.0, vcc
	v_cmp_gt_u32_e32 vcc, s33, v37
	v_lshlrev_b32_e32 v50, 16, v0
	v_fma_f32 v37, -v25, v31, 1.0
	v_cndmask_b32_e64 v24, 0, 1.0, vcc
	v_cmp_gt_u32_e32 vcc, s33, v43
	v_fmac_f32_e32 v31, v37, v31
	v_and_b32_e32 v1, 0xffff0000, v1
	v_cndmask_b32_e64 v30, 0, 1.0, vcc
	v_cmp_gt_u32_e32 vcc, s33, v47
	v_and_b32_e32 v0, 0xffff0000, v0
	v_lshlrev_b32_e32 v27, 16, v21
	v_cndmask_b32_e64 v44, 0, 1.0, vcc
	v_div_scale_f32 v37, vcc, 1.0, v15, 1.0
	v_mul_f32_e32 v46, v37, v31
	v_fma_f32 v47, -v25, v46, v37
	v_fmac_f32_e32 v46, v47, v31
	v_fma_f32 v25, -v25, v46, v37
	v_lshlrev_b32_e32 v26, 16, v20
	v_and_b32_e32 v21, 0xffff0000, v21
	v_and_b32_e32 v20, 0xffff0000, v20
	v_div_fmas_f32 v25, v25, v31, v46
	v_pk_fma_f32 v[8:9], v[14:15], v[0:1], v[8:9] op_sel_hi:[0,1,1]
	v_lshlrev_b32_e32 v34, 16, v16
	v_and_b32_e32 v16, 0xffff0000, v16
	v_lshlrev_b32_e32 v35, 16, v17
	v_and_b32_e32 v17, 0xffff0000, v17
	v_pk_fma_f32 v[8:9], v[24:25], v[20:21], v[8:9] op_sel_hi:[0,1,1]
	v_pk_fma_f32 v[8:9], v[30:31], v[16:17], v[8:9] op_sel_hi:[0,1,1]
	v_lshlrev_b32_e32 v17, 16, v5
	v_lshlrev_b32_e32 v16, 16, v4
	v_and_b32_e32 v5, 0xffff0000, v5
	v_and_b32_e32 v4, 0xffff0000, v4
	v_div_fixup_f32 v46, v25, v15, 1.0
	v_pk_fma_f32 v[4:5], v[44:45], v[4:5], v[8:9] op_sel_hi:[0,1,1]
	v_pk_fma_f32 v[0:1], v[46:47], v[4:5], v[0:1] op_sel_hi:[0,1,1] neg_lo:[0,0,1] neg_hi:[0,0,1]
	v_lshlrev_b32_e32 v5, 16, v3
	v_lshlrev_b32_e32 v4, 16, v2
	v_and_b32_e32 v3, 0xffff0000, v3
	v_and_b32_e32 v2, 0xffff0000, v2
	v_lshlrev_b32_e32 v29, 16, v23
	v_lshlrev_b32_e32 v28, 16, v22
	v_and_b32_e32 v23, 0xffff0000, v23
	v_and_b32_e32 v22, 0xffff0000, v22
	v_pk_fma_f32 v[12:13], v[14:15], v[4:5], v[12:13] op_sel_hi:[0,1,1]
	v_pk_fma_f32 v[10:11], v[14:15], v[2:3], v[10:11] op_sel_hi:[0,1,1]
	v_lshlrev_b32_e32 v42, 16, v18
	v_and_b32_e32 v18, 0xffff0000, v18
	v_lshlrev_b32_e32 v43, 16, v19
	v_and_b32_e32 v19, 0xffff0000, v19
	v_pk_fma_f32 v[32:33], v[14:15], v[50:51], v[32:33] op_sel_hi:[0,1,1]
	v_pk_fma_f32 v[12:13], v[24:25], v[28:29], v[12:13] op_sel_hi:[0,1,1]
	v_pk_fma_f32 v[10:11], v[24:25], v[22:23], v[10:11] op_sel_hi:[0,1,1]
	v_pk_fma_f32 v[26:27], v[24:25], v[26:27], v[32:33] op_sel_hi:[0,1,1]
	v_pk_fma_f32 v[12:13], v[30:31], v[42:43], v[12:13] op_sel_hi:[0,1,1]
	v_pk_fma_f32 v[10:11], v[30:31], v[18:19], v[10:11] op_sel_hi:[0,1,1]
	v_lshlrev_b32_e32 v15, 16, v7
	v_lshlrev_b32_e32 v14, 16, v6
	v_and_b32_e32 v7, 0xffff0000, v7
	v_and_b32_e32 v6, 0xffff0000, v6
	v_pk_fma_f32 v[20:21], v[30:31], v[34:35], v[26:27] op_sel_hi:[0,1,1]
	v_pk_fma_f32 v[12:13], v[44:45], v[14:15], v[12:13] op_sel_hi:[0,1,1]
	v_pk_fma_f32 v[6:7], v[44:45], v[6:7], v[10:11] op_sel_hi:[0,1,1]
	v_pk_fma_f32 v[16:17], v[44:45], v[16:17], v[20:21] op_sel_hi:[0,1,1]
	v_pk_fma_f32 v[4:5], v[46:47], v[12:13], v[4:5] op_sel_hi:[0,1,1] neg_lo:[0,0,1] neg_hi:[0,0,1]
	v_pk_fma_f32 v[2:3], v[46:47], v[6:7], v[2:3] op_sel_hi:[0,1,1] neg_lo:[0,0,1] neg_hi:[0,0,1]
	v_bfe_u32 v10, v1, 16, 1
	v_bfe_u32 v11, v0, 16, 1
	v_pk_fma_f32 v[8:9], v[46:47], v[16:17], v[50:51] op_sel_hi:[0,1,1] neg_lo:[0,0,1] neg_hi:[0,0,1]
	v_bfe_u32 v6, v3, 16, 1
	v_bfe_u32 v7, v2, 16, 1
	v_add3_u32 v0, v0, v11, s5
	v_add3_u32 v1, v1, v10, s5
	v_bfe_u32 v10, v4, 16, 1
	v_bfe_u32 v11, v5, 16, 1
	v_add3_u32 v2, v2, v7, s5
	v_add3_u32 v3, v3, v6, s5
	v_bfe_u32 v6, v8, 16, 1
	v_bfe_u32 v7, v9, 16, 1
	v_add3_u32 v5, v5, v11, s5
	v_add3_u32 v4, v4, v10, s5
	v_add3_u32 v7, v9, v7, s5
	v_add3_u32 v6, v8, v6, s5
	v_lshrrev_b32_e32 v4, 16, v4
	v_lshrrev_b32_e32 v5, 16, v5
	v_ashrrev_i32_e32 v37, 31, v36
	v_lshrrev_b32_e32 v6, 16, v6
	v_lshrrev_b32_e32 v7, 16, v7
	v_and_or_b32 v3, v3, s62, v5
	v_and_or_b32 v2, v2, s62, v4
	v_lshlrev_b64 v[4:5], 12, v[36:37]
	v_and_or_b32 v1, v1, s62, v7
	v_and_or_b32 v0, v0, s62, v6
	v_lshl_add_u64 v[4:5], v[38:39], 0, v[4:5]
	global_store_dwordx4 v[4:5], v[0:3], off
	s_nop 1

; template <int HW> __device__ __forceinline__ void pooled_item(const bf16* __restrict__ ub, bf16* __restrict__ pb, int s) {
;     u32x4 v[2 * HW];
; #pragma unroll
;     for (int j = 0; j < 2 * HW; ++j) { int t = s - HW + j; t = t < 0 ? 0 : (t > S - 1 ? S - 1 : t); v[j] = *(const u32x4*)(ub + (size_t)t * 1024); }
;     float a[8];
; #pragma unroll
;     for (int e = 0; e < 8; ++e) a[e] = 0.f;
; #pragma unroll
;     for (int j = 0; j < 2 * HW; ++j) { const int t = s - HW + j; const float mk = (t >= 0 && t < S) ? 1.f : 0.f;
; #pragma unroll
;         for (int e = 0; e < 4; ++e) { a[2 * e] += mk * __uint_as_float(v[j][e] << 16); a[2 * e + 1] += mk * __uint_as_float(v[j][e] & 0xffff0000u); } }
.LBB0_607:
	s_andn2_saveexec_b64 s[26:27], s[26:27]
	s_mov_b32 s8, 0x40000
	v_cmp_ne_u32_e32 vcc, s8, v2
	s_andn2_b64 s[8:9], s[28:29], exec
	s_and_b64 s[10:11], vcc, exec
	s_or_b64 s[28:29], s[8:9], s[10:11]
	s_mov_b64 s[18:19], exec
	s_or_b64 exec, exec, s[26:27]
	v_add_u32_e32 v53, -2, v36
	v_add_u32_e32 v51, 1, v36
	v_med3_i32 v57, v53, 0, v225
	v_med3_i32 v55, v51, 0, v225
	s_and_saveexec_b64 s[8:9], s[28:29]
	s_xor_b64 s[26:27], exec, s[8:9]
	s_cbranch_execz .LBB0_611
	v_add_u32_e32 v16, -8, v36
	v_med3_i32 v0, v16, 0, v225
	v_lshlrev_b32_e32 v96, 11, v0
	v_lshl_add_u64 v[0:1], v[40:41], 0, v[96:97]
	v_add_u32_e32 v37, -7, v36
	flat_load_dwordx4 v[58:61], v[0:1]
	v_med3_i32 v0, v37, 0, v225
	v_lshlrev_b32_e32 v96, 11, v0
	v_add_u32_e32 v48, -6, v36
	v_lshl_add_u64 v[0:1], v[40:41], 0, v[96:97]
	flat_load_dwordx4 v[62:65], v[0:1]
	v_med3_i32 v0, v48, 0, v225
	v_lshlrev_b32_e32 v96, 11, v0
	v_add_u32_e32 v50, -5, v36
	v_lshl_add_u64 v[0:1], v[40:41], 0, v[96:97]
	v_add_u32_e32 v52, -4, v36
	flat_load_dwordx4 v[66:69], v[0:1]
	v_med3_i32 v0, v50, 0, v225
	v_add_u32_e32 v54, -3, v36
	v_med3_i32 v2, v52, 0, v225
	v_lshlrev_b32_e32 v96, 11, v0
	v_med3_i32 v3, v54, 0, v225
	v_lshl_add_u64 v[0:1], v[40:41], 0, v[96:97]
	v_lshlrev_b32_e32 v96, 11, v2
	v_add_u32_e32 v56, -1, v36
	flat_load_dwordx4 v[72:75], v[0:1]
	v_lshl_add_u64 v[0:1], v[40:41], 0, v[96:97]
	v_lshlrev_b32_e32 v96, 11, v3
	v_med3_i32 v6, v56, 0, v225
	v_lshl_add_u64 v[2:3], v[40:41], 0, v[96:97]
	v_lshlrev_b32_e32 v96, 11, v57
	v_med3_i32 v8, v36, 0, v225
	v_lshl_add_u64 v[4:5], v[40:41], 0, v[96:97]
	v_lshlrev_b32_e32 v96, 11, v6
	v_add_u32_e32 v77, 2, v36
	v_lshl_add_u64 v[6:7], v[40:41], 0, v[96:97]
	v_lshlrev_b32_e32 v96, 11, v8
	v_add_u32_e32 v78, 3, v36
	v_med3_i32 v12, v77, 0, v225
	v_lshl_add_u64 v[8:9], v[40:41], 0, v[96:97]
	v_lshlrev_b32_e32 v96, 11, v55
	v_add_u32_e32 v79, 4, v36
	v_med3_i32 v14, v78, 0, v225
	v_lshl_add_u64 v[10:11], v[40:41], 0, v[96:97]
	v_lshlrev_b32_e32 v96, 11, v12
	v_med3_i32 v15, v79, 0, v225
	v_lshl_add_u64 v[12:13], v[40:41], 0, v[96:97]
	v_lshlrev_b32_e32 v96, 11, v14
	v_lshl_add_u64 v[42:43], v[40:41], 0, v[96:97]
	v_lshlrev_b32_e32 v96, 11, v15
	v_lshl_add_u64 v[14:15], v[40:41], 0, v[96:97]
	flat_load_dwordx4 v[82:85], v[14:15]
	v_add_u32_e32 v86, 5, v36
	v_cmp_gt_u32_e32 vcc, s33, v16
	flat_load_dwordx4 v[28:31], v[0:1]
	flat_load_dwordx4 v[24:27], v[2:3]
	flat_load_dwordx4 v[16:19], v[4:5]
	s_nop 0
	flat_load_dwordx4 v[4:7], v[6:7]
	v_med3_i32 v20, v86, 0, v225
	v_lshlrev_b32_e32 v96, 11, v20
	v_add_u32_e32 v126, 6, v36
	v_lshl_add_u64 v[0:1], v[40:41], 0, v[96:97]
	v_add_u32_e32 v128, 7, v36
	v_med3_i32 v46, v126, 0, v225
	flat_load_dwordx4 v[90:93], v[0:1]
	flat_load_dwordx4 v[32:35], v[8:9]
	flat_load_dwordx4 v[20:23], v[10:11]
	s_nop 0
	flat_load_dwordx4 v[12:15], v[12:13]
	s_nop 0
	flat_load_dwordx4 v[8:11], v[42:43]
	v_med3_i32 v47, v128, 0, v225
	v_lshlrev_b32_e32 v96, 11, v46
	v_lshl_add_u64 v[0:1], v[40:41], 0, v[96:97]
	v_lshlrev_b32_e32 v96, 11, v47
	v_lshl_add_u64 v[2:3], v[40:41], 0, v[96:97]
	flat_load_dwordx4 v[98:101], v[0:1]
	s_nop 0
	flat_load_dwordx4 v[0:3], v[2:3]
	v_cndmask_b32_e64 v44, 0, 1.0, vcc
	v_cmp_gt_u32_e32 vcc, s33, v37
	v_max_i32_e32 v37, 8, v36
	s_andn2_b64 s[18:19], s[18:19], exec
	s_waitcnt vmcnt(0) lgkmcnt(0)
	v_lshlrev_b32_e32 v43, 16, v59
	v_lshlrev_b32_e32 v42, 16, v58
	v_and_b32_e32 v47, 0xffff0000, v59
	v_and_b32_e32 v46, 0xffff0000, v58
	v_lshlrev_b32_e32 v59, 16, v61
	v_lshlrev_b32_e32 v58, 16, v60
	v_pk_fma_f32 v[94:95], v[44:45], v[42:43], 0 op_sel_hi:[0,1,0]
	v_and_b32_e32 v43, 0xffff0000, v61
	v_and_b32_e32 v42, 0xffff0000, v60
	v_pk_fma_f32 v[102:103], v[44:45], v[46:47], 0 op_sel_hi:[0,1,0]
	v_pk_fma_f32 v[70:71], v[44:45], v[58:59], 0 op_sel_hi:[0,1,0]
	v_pk_fma_f32 v[42:43], v[44:45], v[42:43], 0 op_sel_hi:[0,1,0]
	v_cndmask_b32_e64 v44, 0, 1.0, vcc
	v_cmp_gt_u32_e32 vcc, s33, v48
	v_min_i32_e32 v59, 0x1ff8, v36
	v_lshlrev_b32_e32 v104, 16, v62
	v_cndmask_b32_e64 v48, 0, 1.0, vcc
	v_cmp_gt_u32_e32 vcc, s33, v50
	v_and_b32_e32 v106, 0xffff0000, v62
	v_lshlrev_b32_e32 v112, 16, v68
	v_and_b32_e32 v62, 0xffff0000, v68
	v_cndmask_b32_e64 v68, 0, 1.0, vcc
	v_cmp_gt_u32_e32 vcc, s33, v52
	v_sub_u32_e32 v37, v59, v37
	v_add_u32_e32 v37, 16, v37
	v_cndmask_b32_e64 v76, 0, 1.0, vcc
	v_cmp_gt_u32_e32 vcc, s33, v54
	v_lshlrev_b32_e32 v118, 16, v74
	v_and_b32_e32 v80, 0xffff0000, v74
	v_cndmask_b32_e64 v74, 0, 1.0, vcc
	v_cmp_gt_u32_e32 vcc, s33, v53
	v_cvt_f32_i32_e32 v37, v37
	v_lshlrev_b32_e32 v88, 16, v64
	v_and_b32_e32 v46, 0xffff0000, v64
	v_cndmask_b32_e64 v64, 0, 1.0, vcc
	v_cmp_gt_u32_e32 vcc, s33, v56
	v_div_scale_f32 v59, s[8:9], v37, v37, 1.0
	s_nop 0
	v_cndmask_b32_e64 v60, 0, 1.0, vcc
	v_cmp_gt_u32_e32 vcc, s33, v36
	v_rcp_f32_e32 v61, v59
	v_lshlrev_b32_e32 v89, 16, v65
	v_cndmask_b32_e64 v50, 0, 1.0, vcc
	v_cmp_gt_u32_e32 vcc, s33, v51
	v_and_b32_e32 v47, 0xffff0000, v65
	v_lshlrev_b32_e32 v108, 16, v66
	v_cndmask_b32_e64 v52, 0, 1.0, vcc
	v_cmp_gt_u32_e32 vcc, s33, v77
	v_and_b32_e32 v110, 0xffff0000, v66
	v_lshlrev_b32_e32 v114, 16, v72
	v_cndmask_b32_e64 v54, 0, 1.0, vcc
	v_cmp_gt_u32_e32 vcc, s33, v78
	v_and_b32_e32 v116, 0xffff0000, v72
	v_lshlrev_b32_e32 v66, 16, v84
	v_cndmask_b32_e64 v58, 0, 1.0, vcc
	v_cmp_gt_u32_e32 vcc, s33, v79
	v_and_b32_e32 v72, 0xffff0000, v84
	v_fma_f32 v65, -v59, v61, 1.0
	v_cndmask_b32_e64 v56, 0, 1.0, vcc
	v_cmp_gt_u32_e32 vcc, s33, v86
	v_fmac_f32_e32 v61, v65, v61
	v_lshlrev_b32_e32 v105, 16, v63
	v_cndmask_b32_e64 v78, 0, 1.0, vcc
	v_cmp_gt_u32_e32 vcc, s33, v126
	v_and_b32_e32 v107, 0xffff0000, v63
	v_lshlrev_b32_e32 v113, 16, v69
; template <int HW> __device__ __forceinline__ void pooled_item(const bf16* __restrict__ ub, bf16* __restrict__ pb, int s) {
;     ...
;     for (int j = 0; j < 2 * HW; ++j) { const int t = s - HW + j; const float mk = (t >= 0 && t < S) ? 1.f : 0.f;
; #pragma unroll
;         for (int e = 0; e < 4; ++e) { a[2 * e] += mk * __uint_as_float(v[j][e] << 16); a[2 * e + 1] += mk * __uint_as_float(v[j][e] & 0xffff0000u); } }
;     const int lo = (s - HW) < 0 ? 0 : (s - HW), hi = (s + HW) > S ? S : (s + HW);
;     const float ic = 1.0f / (float)(hi - lo);
	v_cndmask_b32_e64 v84, 0, 1.0, vcc
	v_cmp_gt_u32_e32 vcc, s33, v128
	v_and_b32_e32 v63, 0xffff0000, v69
	v_lshlrev_b32_e32 v109, 16, v67
	v_cndmask_b32_e64 v96, 0, 1.0, vcc
	v_div_scale_f32 v65, vcc, 1.0, v37, 1.0
	v_mul_f32_e32 v69, v65, v61
	v_lshlrev_b32_e32 v119, 16, v75
	v_and_b32_e32 v81, 0xffff0000, v75
	v_fma_f32 v75, -v59, v69, v65
	v_pk_fma_f32 v[94:95], v[44:45], v[104:105], v[94:95] op_sel_hi:[0,1,1]
	v_and_b32_e32 v111, 0xffff0000, v67
	v_lshlrev_b32_e32 v115, 16, v73
	v_fmac_f32_e32 v69, v75, v61
	v_pk_fma_f32 v[94:95], v[48:49], v[108:109], v[94:95] op_sel_hi:[0,1,1]
	v_pk_fma_f32 v[102:103], v[44:45], v[106:107], v[102:103] op_sel_hi:[0,1,1]
	v_and_b32_e32 v117, 0xffff0000, v73
	v_pk_fma_f32 v[94:95], v[68:69], v[114:115], v[94:95] op_sel_hi:[0,1,1]
	v_lshlrev_b32_e32 v105, 16, v29
	v_lshlrev_b32_e32 v104, 16, v28
	v_pk_fma_f32 v[102:103], v[48:49], v[110:111], v[102:103] op_sel_hi:[0,1,1]
	v_pk_fma_f32 v[94:95], v[76:77], v[104:105], v[94:95] op_sel_hi:[0,1,1]
	v_lshlrev_b32_e32 v105, 16, v25
	v_lshlrev_b32_e32 v104, 16, v24
	v_pk_fma_f32 v[102:103], v[68:69], v[116:117], v[102:103] op_sel_hi:[0,1,1]
	v_and_b32_e32 v29, 0xffff0000, v29
	v_and_b32_e32 v28, 0xffff0000, v28
	v_pk_fma_f32 v[94:95], v[74:75], v[104:105], v[94:95] op_sel_hi:[0,1,1]
	v_lshlrev_b32_e32 v105, 16, v17
	v_lshlrev_b32_e32 v104, 16, v16
	v_pk_fma_f32 v[28:29], v[76:77], v[28:29], v[102:103] op_sel_hi:[0,1,1]
	v_and_b32_e32 v25, 0xffff0000, v25
	v_and_b32_e32 v24, 0xffff0000, v24
	v_pk_fma_f32 v[94:95], v[64:65], v[104:105], v[94:95] op_sel_hi:[0,1,1]
	v_lshlrev_b32_e32 v105, 16, v5
	v_lshlrev_b32_e32 v104, 16, v4
	v_pk_fma_f32 v[24:25], v[74:75], v[24:25], v[28:29] op_sel_hi:[0,1,1]
	v_and_b32_e32 v17, 0xffff0000, v17
	v_and_b32_e32 v16, 0xffff0000, v16
	v_lshlrev_b32_e32 v131, 16, v33
	v_lshlrev_b32_e32 v130, 16, v32
	v_pk_fma_f32 v[94:95], v[60:61], v[104:105], v[94:95] op_sel_hi:[0,1,1]
	v_pk_fma_f32 v[16:17], v[64:65], v[16:17], v[24:25] op_sel_hi:[0,1,1]
	v_and_b32_e32 v5, 0xffff0000, v5
	v_and_b32_e32 v4, 0xffff0000, v4
	v_and_b32_e32 v33, 0xffff0000, v33
	v_and_b32_e32 v32, 0xffff0000, v32
	v_lshlrev_b32_e32 v105, 16, v21
	v_lshlrev_b32_e32 v104, 16, v20
	v_pk_fma_f32 v[94:95], v[50:51], v[130:131], v[94:95] op_sel_hi:[0,1,1]
	v_pk_fma_f32 v[4:5], v[60:61], v[4:5], v[16:17] op_sel_hi:[0,1,1]
	v_fma_f32 v59, -v59, v69, v65
	v_lshlrev_b32_e32 v109, 16, v13
	v_lshlrev_b32_e32 v108, 16, v12
	v_pk_fma_f32 v[94:95], v[52:53], v[104:105], v[94:95] op_sel_hi:[0,1,1]
	v_and_b32_e32 v17, 0xffff0000, v21
	v_and_b32_e32 v16, 0xffff0000, v20
	v_pk_fma_f32 v[4:5], v[50:51], v[32:33], v[4:5] op_sel_hi:[0,1,1]
	v_div_fmas_f32 v59, v59, v61, v69
	v_lshlrev_b32_e32 v115, 16, v9
	v_lshlrev_b32_e32 v114, 16, v8
	v_pk_fma_f32 v[94:95], v[54:55], v[108:109], v[94:95] op_sel_hi:[0,1,1]
	v_and_b32_e32 v13, 0xffff0000, v13
	v_and_b32_e32 v12, 0xffff0000, v12
	v_pk_fma_f32 v[4:5], v[52:53], v[16:17], v[4:5] op_sel_hi:[0,1,1]
	v_pk_fma_f32 v[16:17], v[44:45], v[88:89], v[70:71] op_sel_hi:[0,1,1]
	v_lshlrev_b32_e32 v121, 16, v83
	v_lshlrev_b32_e32 v120, 16, v82
	v_pk_fma_f32 v[94:95], v[58:59], v[114:115], v[94:95] op_sel_hi:[0,1,1]
	v_and_b32_e32 v9, 0xffff0000, v9
	v_and_b32_e32 v8, 0xffff0000, v8
	v_pk_fma_f32 v[4:5], v[54:55], v[12:13], v[4:5] op_sel_hi:[0,1,1]
	v_pk_fma_f32 v[16:17], v[48:49], v[112:113], v[16:17] op_sel_hi:[0,1,1]
	v_and_b32_e32 v123, 0xffff0000, v83
	v_and_b32_e32 v122, 0xffff0000, v82
	v_lshlrev_b32_e32 v125, 16, v91
	v_lshlrev_b32_e32 v124, 16, v90
	v_pk_fma_f32 v[4:5], v[58:59], v[8:9], v[4:5] op_sel_hi:[0,1,1]
	v_pk_fma_f32 v[8:9], v[56:57], v[120:121], v[94:95] op_sel_hi:[0,1,1]
	v_pk_fma_f32 v[16:17], v[68:69], v[118:119], v[16:17] op_sel_hi:[0,1,1]
	v_lshlrev_b32_e32 v21, 16, v31
	v_lshlrev_b32_e32 v20, 16, v30
	v_and_b32_e32 v91, 0xffff0000, v91
	v_and_b32_e32 v90, 0xffff0000, v90
	v_lshlrev_b32_e32 v83, 16, v93
	v_lshlrev_b32_e32 v82, 16, v92
	v_and_b32_e32 v87, 0xffff0000, v93
	v_and_b32_e32 v86, 0xffff0000, v92
	v_lshlrev_b32_e32 v92, 16, v98
	v_lshlrev_b32_e32 v93, 16, v99
	v_pk_fma_f32 v[4:5], v[56:57], v[122:123], v[4:5] op_sel_hi:[0,1,1]
	v_pk_fma_f32 v[8:9], v[78:79], v[124:125], v[8:9] op_sel_hi:[0,1,1]
	v_pk_fma_f32 v[16:17], v[76:77], v[20:21], v[16:17] op_sel_hi:[0,1,1]
	v_lshlrev_b32_e32 v21, 16, v27
	v_lshlrev_b32_e32 v20, 16, v26
	v_and_b32_e32 v98, 0xffff0000, v98
	v_and_b32_e32 v99, 0xffff0000, v99
	v_pk_fma_f32 v[4:5], v[78:79], v[90:91], v[4:5] op_sel_hi:[0,1,1]
	v_pk_fma_f32 v[8:9], v[84:85], v[92:93], v[8:9] op_sel_hi:[0,1,1]
	v_lshlrev_b32_e32 v13, 16, v1
	v_lshlrev_b32_e32 v12, 16, v0
	v_pk_fma_f32 v[16:17], v[74:75], v[20:21], v[16:17] op_sel_hi:[0,1,1]
	v_lshlrev_b32_e32 v21, 16, v19
	v_lshlrev_b32_e32 v20, 16, v18
	v_div_fixup_f32 v128, v59, v37, 1.0
	v_pk_fma_f32 v[4:5], v[84:85], v[98:99], v[4:5] op_sel_hi:[0,1,1]
	v_pk_fma_f32 v[8:9], v[96:97], v[12:13], v[8:9] op_sel_hi:[0,1,1]
	v_and_b32_e32 v1, 0xffff0000, v1
	v_and_b32_e32 v0, 0xffff0000, v0
	v_pk_fma_f32 v[16:17], v[64:65], v[20:21], v[16:17] op_sel_hi:[0,1,1]
	v_lshlrev_b32_e32 v21, 16, v7
	v_lshlrev_b32_e32 v20, 16, v6
	v_pk_fma_f32 v[0:1], v[96:97], v[0:1], v[4:5] op_sel_hi:[0,1,1]
	v_pk_fma_f32 v[4:5], v[128:129], v[8:9], v[130:131] op_sel_hi:[0,1,1] neg_lo:[0,0,1] neg_hi:[0,0,1]
	v_lshlrev_b32_e32 v9, 16, v35
	v_lshlrev_b32_e32 v8, 16, v34
	v_pk_fma_f32 v[16:17], v[60:61], v[20:21], v[16:17] op_sel_hi:[0,1,1]
	v_lshlrev_b32_e32 v21, 16, v23
	v_lshlrev_b32_e32 v20, 16, v22
	v_pk_fma_f32 v[16:17], v[50:51], v[8:9], v[16:17] op_sel_hi:[0,1,1]
	v_pk_fma_f32 v[16:17], v[52:53], v[20:21], v[16:17] op_sel_hi:[0,1,1]
	v_pk_fma_f32 v[20:21], v[44:45], v[46:47], v[42:43] op_sel_hi:[0,1,1]
; __device__ __forceinline__ unsigned pk2(float lo, float hi) { return f2bf(lo) | (f2bf(hi) << 16); }
; template <int HW> __device__ __forceinline__ void pooled_item(const bf16* __restrict__ ub, bf16* __restrict__ pb, int s) {
;     ...
;     for (int j = 0; j < 2 * HW; ++j) { const int t = s - HW + j; const float mk = (t >= 0 && t < S) ? 1.f : 0.f;
; #pragma unroll
;         for (int e = 0; e < 4; ++e) { a[2 * e] += mk * __uint_as_float(v[j][e] << 16); a[2 * e + 1] += mk * __uint_as_float(v[j][e] & 0xffff0000u); } }
;     const int lo = (s - HW) < 0 ? 0 : (s - HW), hi = (s + HW) > S ? S : (s + HW);
;     const float ic = 1.0f / (float)(hi - lo);
;     const u32x4 c = v[HW];
;     u32x4 ov;
; #pragma unroll
;     for (int e = 0; e < 4; ++e) ov[e] = pk2(a[2 * e] * ic - __uint_as_float(c[e] << 16), a[2 * e + 1] * ic - __uint_as_float(c[e] & 0xffff0000u));
;     asm volatile("global_store_dwordx4 %0, %1, off sc1\n\ts_nop 1" :: "v"(pb + (size_t)s * D), "v"(ov) : "memory");
	v_lshlrev_b32_e32 v25, 16, v15
	v_lshlrev_b32_e32 v24, 16, v14
	v_pk_fma_f32 v[20:21], v[48:49], v[62:63], v[20:21] op_sel_hi:[0,1,1]
	v_pk_fma_f32 v[16:17], v[54:55], v[24:25], v[16:17] op_sel_hi:[0,1,1]
	v_pk_fma_f32 v[20:21], v[68:69], v[80:81], v[20:21] op_sel_hi:[0,1,1]
	v_and_b32_e32 v25, 0xffff0000, v31
	v_and_b32_e32 v24, 0xffff0000, v30
	v_pk_fma_f32 v[20:21], v[76:77], v[24:25], v[20:21] op_sel_hi:[0,1,1]
	v_and_b32_e32 v25, 0xffff0000, v27
	v_and_b32_e32 v24, 0xffff0000, v26
	v_pk_fma_f32 v[20:21], v[74:75], v[24:25], v[20:21] op_sel_hi:[0,1,1]
	v_and_b32_e32 v19, 0xffff0000, v19
	v_and_b32_e32 v18, 0xffff0000, v18
	v_pk_fma_f32 v[18:19], v[64:65], v[18:19], v[20:21] op_sel_hi:[0,1,1]
	v_and_b32_e32 v7, 0xffff0000, v7
	v_and_b32_e32 v6, 0xffff0000, v6
	v_and_b32_e32 v13, 0xffff0000, v35
	v_and_b32_e32 v12, 0xffff0000, v34
	v_pk_fma_f32 v[6:7], v[60:61], v[6:7], v[18:19] op_sel_hi:[0,1,1]
	v_and_b32_e32 v19, 0xffff0000, v23
	v_and_b32_e32 v18, 0xffff0000, v22
	v_pk_fma_f32 v[6:7], v[50:51], v[12:13], v[6:7] op_sel_hi:[0,1,1]
	v_and_b32_e32 v15, 0xffff0000, v15
	v_and_b32_e32 v14, 0xffff0000, v14
	v_pk_fma_f32 v[6:7], v[52:53], v[18:19], v[6:7] op_sel_hi:[0,1,1]
	v_lshlrev_b32_e32 v29, 16, v11
	v_lshlrev_b32_e32 v28, 16, v10
	v_and_b32_e32 v11, 0xffff0000, v11
	v_and_b32_e32 v10, 0xffff0000, v10
	v_pk_fma_f32 v[6:7], v[54:55], v[14:15], v[6:7] op_sel_hi:[0,1,1]
	v_and_b32_e32 v73, 0xffff0000, v85
	v_pk_fma_f32 v[6:7], v[58:59], v[10:11], v[6:7] op_sel_hi:[0,1,1]
	v_lshlrev_b32_e32 v67, 16, v85
	v_pk_fma_f32 v[16:17], v[58:59], v[28:29], v[16:17] op_sel_hi:[0,1,1]
	v_pk_fma_f32 v[6:7], v[56:57], v[72:73], v[6:7] op_sel_hi:[0,1,1]
	v_lshlrev_b32_e32 v126, 16, v100
	v_and_b32_e32 v100, 0xffff0000, v100
	v_lshlrev_b32_e32 v127, 16, v101
	v_and_b32_e32 v101, 0xffff0000, v101
	v_pk_fma_f32 v[10:11], v[56:57], v[66:67], v[16:17] op_sel_hi:[0,1,1]
	v_pk_fma_f32 v[6:7], v[78:79], v[86:87], v[6:7] op_sel_hi:[0,1,1]
	v_pk_fma_f32 v[10:11], v[78:79], v[82:83], v[10:11] op_sel_hi:[0,1,1]
	v_pk_fma_f32 v[6:7], v[84:85], v[100:101], v[6:7] op_sel_hi:[0,1,1]
	v_lshlrev_b32_e32 v15, 16, v3
	v_lshlrev_b32_e32 v14, 16, v2
	v_and_b32_e32 v3, 0xffff0000, v3
	v_and_b32_e32 v2, 0xffff0000, v2
	v_pk_fma_f32 v[10:11], v[84:85], v[126:127], v[10:11] op_sel_hi:[0,1,1]
	v_pk_fma_f32 v[2:3], v[96:97], v[2:3], v[6:7] op_sel_hi:[0,1,1]
	v_pk_fma_f32 v[10:11], v[96:97], v[14:15], v[10:11] op_sel_hi:[0,1,1]
	v_pk_fma_f32 v[2:3], v[128:129], v[2:3], v[12:13] op_sel_hi:[0,1,1] neg_lo:[0,0,1] neg_hi:[0,0,1]
	v_pk_fma_f32 v[0:1], v[128:129], v[0:1], v[32:33] op_sel_hi:[0,1,1] neg_lo:[0,0,1] neg_hi:[0,0,1]
	v_pk_fma_f32 v[6:7], v[128:129], v[10:11], v[8:9] op_sel_hi:[0,1,1] neg_lo:[0,0,1] neg_hi:[0,0,1]
	v_bfe_u32 v8, v3, 16, 1
	v_bfe_u32 v9, v2, 16, 1
	v_bfe_u32 v10, v1, 16, 1
	v_bfe_u32 v11, v0, 16, 1
	v_add3_u32 v2, v2, v9, s5
	v_add3_u32 v3, v3, v8, s5
	v_bfe_u32 v8, v4, 16, 1
	v_bfe_u32 v9, v5, 16, 1
	v_add3_u32 v0, v0, v11, s5
	v_add3_u32 v1, v1, v10, s5
	v_bfe_u32 v10, v6, 16, 1
	v_bfe_u32 v11, v7, 16, 1
	v_add3_u32 v5, v5, v9, s5
	v_add3_u32 v4, v4, v8, s5
	v_add3_u32 v7, v7, v11, s5
	v_add3_u32 v6, v6, v10, s5
	v_lshrrev_b32_e32 v4, 16, v4
	v_lshrrev_b32_e32 v5, 16, v5
	v_ashrrev_i32_e32 v37, 31, v36
	v_lshrrev_b32_e32 v6, 16, v6
	v_lshrrev_b32_e32 v7, 16, v7
	v_and_or_b32 v1, v1, s62, v5
	v_and_or_b32 v0, v0, s62, v4
	v_lshlrev_b64 v[4:5], 12, v[36:37]
	v_and_or_b32 v3, v3, s62, v7
	v_and_or_b32 v2, v2, s62, v6
	v_lshl_add_u64 v[4:5], v[38:39], 0, v[4:5]
	global_store_dwordx4 v[4:5], v[0:3], off
	s_nop 1
; __device__ __forceinline__ unsigned pk2(float lo, float hi) { return f2bf(lo) | (f2bf(hi) << 16); }
; template <int HW> __device__ __forceinline__ void pooled_item(const bf16* __restrict__ ub, bf16* __restrict__ pb, int s) {
;     u32x4 v[2 * HW];
; #pragma unroll
;     for (int j = 0; j < 2 * HW; ++j) { int t = s - HW + j; t = t < 0 ? 0 : (t > S - 1 ? S - 1 : t); v[j] = *(const u32x4*)(ub + (size_t)t * 1024); }
;     float a[8];
; #pragma unroll
;     for (int e = 0; e < 8; ++e) a[e] = 0.f;
; #pragma unroll
;     for (int j = 0; j < 2 * HW; ++j) { const int t = s - HW + j; const float mk = (t >= 0 && t < S) ? 1.f : 0.f;
; #pragma unroll
;         for (int e = 0; e < 4; ++e) { a[2 * e] += mk * __uint_as_float(v[j][e] << 16); a[2 * e + 1] += mk * __uint_as_float(v[j][e] & 0xffff0000u); } }
;     const int lo = (s - HW) < 0 ? 0 : (s - HW), hi = (s + HW) > S ? S : (s + HW);
;     const float ic = 1.0f / (float)(hi - lo);
;     const u32x4 c = v[HW];
;     u32x4 ov;
; #pragma unroll
;     for (int e = 0; e < 4; ++e) ov[e] = pk2(a[2 * e] * ic - __uint_as_float(c[e] << 16), a[2 * e + 1] * ic - __uint_as_float(c[e] & 0xffff0000u));
;     asm volatile("global_store_dwordx4 %0, %1, off sc1\n\ts_nop 1" :: "v"(pb + (size_t)s * D), "v"(ov) : "memory");
.LBB0_611:
	s_or_b64 exec, exec, s[26:27]
	s_and_saveexec_b64 s[26:27], s[18:19]
	s_cbranch_execz .LBB0_613
	v_add_u32_e32 v17, -1, v36
	v_lshlrev_b32_e32 v96, 11, v57
	v_med3_i32 v4, v17, 0, v225
	v_lshl_add_u64 v[0:1], v[40:41], 0, v[96:97]
	v_lshlrev_b32_e32 v96, 11, v4
	v_med3_i32 v8, v36, 0, v225
	flat_load_dwordx4 v[0:3], v[0:1]
	v_lshl_add_u64 v[4:5], v[40:41], 0, v[96:97]
	v_lshlrev_b32_e32 v96, 11, v8
	flat_load_dwordx4 v[4:7], v[4:5]
	v_lshl_add_u64 v[8:9], v[40:41], 0, v[96:97]
	v_lshlrev_b32_e32 v96, 11, v55
	flat_load_dwordx4 v[8:11], v[8:9]
	v_lshl_add_u64 v[12:13], v[40:41], 0, v[96:97]
	flat_load_dwordx4 v[12:15], v[12:13]
	v_max_i32_e32 v19, 2, v36
	v_min_i32_e32 v20, 0x1ffe, v36
	v_sub_u32_e32 v19, v20, v19
	v_add_u32_e32 v19, 4, v19
	v_cvt_f32_i32_e32 v19, v19
	v_cmp_gt_u32_e32 vcc, s33, v53
	v_ashrrev_i32_e32 v37, 31, v36
	v_div_scale_f32 v21, s[8:9], v19, v19, 1.0
	v_rcp_f32_e32 v23, v21
	v_cndmask_b32_e64 v16, 0, 1.0, vcc
	v_cmp_gt_u32_e32 vcc, s33, v36
	v_fma_f32 v24, -v21, v23, 1.0
	s_nop 0
	v_cndmask_b32_e64 v18, 0, 1.0, vcc
	v_cmp_gt_u32_e32 vcc, s33, v51
	v_fmac_f32_e32 v23, v24, v23
	s_waitcnt vmcnt(0) lgkmcnt(0)
	v_lshlrev_b32_e32 v27, 16, v1
	v_cndmask_b32_e64 v20, 0, 1.0, vcc
	v_cmp_gt_u32_e32 vcc, s33, v17
	v_lshlrev_b32_e32 v26, 16, v0
	v_and_b32_e32 v1, 0xffff0000, v1
	v_cndmask_b32_e64 v22, 0, 1.0, vcc
	v_div_scale_f32 v17, vcc, 1.0, v19, 1.0
	v_mul_f32_e32 v24, v17, v23
	v_fma_f32 v25, -v21, v24, v17
	v_fmac_f32_e32 v24, v25, v23
	v_fma_f32 v17, -v21, v24, v17
	v_div_fmas_f32 v17, v17, v23, v24
	v_and_b32_e32 v0, 0xffff0000, v0
	v_lshlrev_b32_e32 v29, 16, v3
	v_lshlrev_b32_e32 v28, 16, v2
	v_and_b32_e32 v3, 0xffff0000, v3
	v_and_b32_e32 v2, 0xffff0000, v2
	v_div_fixup_f32 v24, v17, v19, 1.0
	v_pk_fma_f32 v[26:27], v[16:17], v[26:27], 0 op_sel_hi:[0,1,0]
	v_pk_fma_f32 v[0:1], v[16:17], v[0:1], 0 op_sel_hi:[0,1,0]
	v_pk_fma_f32 v[28:29], v[16:17], v[28:29], 0 op_sel_hi:[0,1,0]
	v_pk_fma_f32 v[2:3], v[16:17], v[2:3], 0 op_sel_hi:[0,1,0]
	v_lshlrev_b32_e32 v17, 16, v5
	v_lshlrev_b32_e32 v16, 16, v4
	v_and_b32_e32 v5, 0xffff0000, v5
	v_and_b32_e32 v4, 0xffff0000, v4
	v_lshlrev_b32_e32 v31, 16, v7
	v_lshlrev_b32_e32 v30, 16, v6
	v_and_b32_e32 v7, 0xffff0000, v7
	v_and_b32_e32 v6, 0xffff0000, v6
	v_lshlrev_b32_e32 v32, 16, v8
	v_and_b32_e32 v8, 0xffff0000, v8
	v_lshlrev_b32_e32 v33, 16, v9
	v_and_b32_e32 v9, 0xffff0000, v9
	v_pk_fma_f32 v[16:17], v[22:23], v[16:17], v[26:27] op_sel_hi:[0,1,1]
	v_pk_fma_f32 v[0:1], v[22:23], v[4:5], v[0:1] op_sel_hi:[0,1,1]
	v_pk_fma_f32 v[2:3], v[22:23], v[6:7], v[2:3] op_sel_hi:[0,1,1]
	v_pk_fma_f32 v[6:7], v[18:19], v[32:33], v[16:17] op_sel_hi:[0,1,1]
	v_pk_fma_f32 v[0:1], v[18:19], v[8:9], v[0:1] op_sel_hi:[0,1,1]
	v_lshlrev_b32_e32 v17, 16, v13
	v_lshlrev_b32_e32 v16, 16, v12
	v_and_b32_e32 v13, 0xffff0000, v13
	v_and_b32_e32 v12, 0xffff0000, v12
	v_lshlrev_b32_e32 v34, 16, v10
	v_and_b32_e32 v10, 0xffff0000, v10
	v_lshlrev_b32_e32 v35, 16, v11
	v_and_b32_e32 v11, 0xffff0000, v11
	v_pk_fma_f32 v[4:5], v[22:23], v[30:31], v[28:29] op_sel_hi:[0,1,1]
	v_pk_fma_f32 v[0:1], v[20:21], v[12:13], v[0:1] op_sel_hi:[0,1,1]
	v_pk_fma_f32 v[4:5], v[18:19], v[34:35], v[4:5] op_sel_hi:[0,1,1]
	v_pk_fma_f32 v[2:3], v[18:19], v[10:11], v[2:3] op_sel_hi:[0,1,1]
	v_lshlrev_b32_e32 v19, 16, v15
	v_lshlrev_b32_e32 v18, 16, v14
	v_pk_fma_f32 v[0:1], v[24:25], v[0:1], v[8:9] op_sel_hi:[0,1,1] neg_lo:[0,0,1] neg_hi:[0,0,1]
	v_and_b32_e32 v9, 0xffff0000, v15
	v_and_b32_e32 v8, 0xffff0000, v14
	v_pk_fma_f32 v[4:5], v[20:21], v[18:19], v[4:5] op_sel_hi:[0,1,1]
	v_pk_fma_f32 v[2:3], v[20:21], v[8:9], v[2:3] op_sel_hi:[0,1,1]
	v_pk_fma_f32 v[6:7], v[20:21], v[16:17], v[6:7] op_sel_hi:[0,1,1]
	v_pk_fma_f32 v[4:5], v[24:25], v[4:5], v[34:35] op_sel_hi:[0,1,1] neg_lo:[0,0,1] neg_hi:[0,0,1]
	v_pk_fma_f32 v[2:3], v[24:25], v[2:3], v[10:11] op_sel_hi:[0,1,1] neg_lo:[0,0,1] neg_hi:[0,0,1]
	v_bfe_u32 v10, v1, 16, 1
	v_bfe_u32 v11, v0, 16, 1
	v_pk_fma_f32 v[6:7], v[24:25], v[6:7], v[32:33] op_sel_hi:[0,1,1] neg_lo:[0,0,1] neg_hi:[0,0,1]
	v_bfe_u32 v8, v3, 16, 1
	v_bfe_u32 v9, v2, 16, 1
	v_add3_u32 v0, v0, v11, s5
	v_add3_u32 v1, v1, v10, s5
	v_bfe_u32 v10, v4, 16, 1
	v_bfe_u32 v11, v5, 16, 1
	v_add3_u32 v2, v2, v9, s5
	v_add3_u32 v3, v3, v8, s5
	v_bfe_u32 v8, v6, 16, 1
	v_bfe_u32 v9, v7, 16, 1
	v_add3_u32 v5, v5, v11, s5
	v_add3_u32 v4, v4, v10, s5
	v_add3_u32 v7, v7, v9, s5
	v_add3_u32 v6, v6, v8, s5
	v_lshrrev_b32_e32 v4, 16, v4
	v_lshrrev_b32_e32 v5, 16, v5
	v_lshrrev_b32_e32 v6, 16, v6
	v_lshrrev_b32_e32 v7, 16, v7
	v_and_or_b32 v3, v3, s62, v5
	v_and_or_b32 v2, v2, s62, v4
	v_lshlrev_b64 v[4:5], 12, v[36:37]
	v_and_or_b32 v1, v1, s62, v7
	v_and_or_b32 v0, v0, s62, v6
	v_lshl_add_u64 v[4:5], v[38:39], 0, v[4:5]
	global_store_dwordx4 v[4:5], v[0:3], off
	s_nop 1

; __device__ __forceinline__ unsigned pk2(float lo, float hi) { return f2bf(lo) | (f2bf(hi) << 16); }
; template <int HW> __device__ __forceinline__ void pooled_item(const bf16* __restrict__ ub, bf16* __restrict__ pb, int s) {
;     u32x4 v[2 * HW];
; #pragma unroll
;     for (int j = 0; j < 2 * HW; ++j) { int t = s - HW + j; t = t < 0 ? 0 : (t > S - 1 ? S - 1 : t); v[j] = *(const u32x4*)(ub + (size_t)t * 1024); }
;     float a[8];
; #pragma unroll
;     for (int e = 0; e < 8; ++e) a[e] = 0.f;
; #pragma unroll
;     for (int j = 0; j < 2 * HW; ++j) { const int t = s - HW + j; const float mk = (t >= 0 && t < S) ? 1.f : 0.f;
; #pragma unroll
;         for (int e = 0; e < 4; ++e) { a[2 * e] += mk * __uint_as_float(v[j][e] << 16); a[2 * e + 1] += mk * __uint_as_float(v[j][e] & 0xffff0000u); } }
;     const int lo = (s - HW) < 0 ? 0 : (s - HW), hi = (s + HW) > S ? S : (s + HW);
;     const float ic = 1.0f / (float)(hi - lo);
;     const u32x4 c = v[HW];
;     u32x4 ov;
; #pragma unroll
;     for (int e = 0; e < 4; ++e) ov[e] = pk2(a[2 * e] * ic - __uint_as_float(c[e] << 16), a[2 * e + 1] * ic - __uint_as_float(c[e] & 0xffff0000u));
;     asm volatile("global_store_dwordx4 %0, %1, off sc1\n\ts_nop 1" :: "v"(pb + (size_t)s * D), "v"(ov) : "memory");
.LBB0_614:
	s_andn2_saveexec_b64 s[16:17], s[16:17]
	s_cbranch_execz .LBB0_601
	v_add_u32_e32 v10, -1, v36
	v_lshl_add_u64 v[4:5], v[0:1], 1, s[66:67]
	v_med3_i32 v0, v10, 0, v225
	v_lshlrev_b32_e32 v96, 11, v0
	v_med3_i32 v6, v36, 0, v225
	v_lshl_add_u64 v[0:1], v[40:41], 0, v[96:97]
	v_lshlrev_b32_e32 v96, 11, v6
	flat_load_dwordx4 v[0:3], v[0:1]
	v_lshl_add_u64 v[6:7], v[40:41], 0, v[96:97]
	flat_load_dwordx4 v[6:9], v[6:7]
	v_max_i32_e32 v11, 1, v36
	v_min_i32_e32 v17, 0x1fff, v36
	v_sub_u32_e32 v11, v17, v11
	v_add_u32_e32 v11, 2, v11
	v_cvt_f32_i32_e32 v11, v11
	v_cmp_gt_u32_e32 vcc, s33, v10
	v_ashrrev_i32_e32 v37, 31, v36
	v_div_scale_f32 v17, s[8:9], v11, v11, 1.0
	v_rcp_f32_e32 v18, v17
	v_cndmask_b32_e64 v10, 0, 1.0, vcc
	v_cmp_gt_u32_e32 vcc, s33, v36
	v_fma_f32 v19, -v17, v18, 1.0
	s_nop 0
	v_cndmask_b32_e64 v16, 0, 1.0, vcc
	v_fmac_f32_e32 v18, v19, v18
	v_div_scale_f32 v19, vcc, 1.0, v11, 1.0
	v_mul_f32_e32 v20, v19, v18
	v_fma_f32 v21, -v17, v20, v19
	v_fmac_f32_e32 v20, v21, v18
	v_fma_f32 v17, -v17, v20, v19
	v_div_fmas_f32 v17, v17, v18, v20
	v_div_fixup_f32 v18, v17, v11, 1.0
	s_waitcnt vmcnt(0) lgkmcnt(0)
	v_lshlrev_b32_e32 v12, 16, v0
	v_and_b32_e32 v0, 0xffff0000, v0
	v_lshlrev_b32_e32 v13, 16, v1
	v_and_b32_e32 v1, 0xffff0000, v1
	v_pk_fma_f32 v[0:1], v[10:11], v[0:1], 0 op_sel_hi:[0,1,0]
	v_lshlrev_b32_e32 v21, 16, v7
	v_lshlrev_b32_e32 v20, 16, v6
	v_and_b32_e32 v7, 0xffff0000, v7
	v_and_b32_e32 v6, 0xffff0000, v6
	v_lshlrev_b32_e32 v14, 16, v2
	v_and_b32_e32 v2, 0xffff0000, v2
	v_lshlrev_b32_e32 v15, 16, v3
	v_and_b32_e32 v3, 0xffff0000, v3
	v_pk_fma_f32 v[0:1], v[16:17], v[6:7], v[0:1] op_sel_hi:[0,1,1]
	v_pk_fma_f32 v[12:13], v[10:11], v[12:13], 0 op_sel_hi:[0,1,0]
	v_pk_fma_f32 v[0:1], v[18:19], v[0:1], v[6:7] op_sel_hi:[0,1,1] neg_lo:[0,0,1] neg_hi:[0,0,1]
	v_pk_fma_f32 v[6:7], v[10:11], v[14:15], 0 op_sel_hi:[0,1,0]
	v_pk_fma_f32 v[2:3], v[10:11], v[2:3], 0 op_sel_hi:[0,1,0]
	v_lshlrev_b32_e32 v11, 16, v9
	v_lshlrev_b32_e32 v10, 16, v8
	v_and_b32_e32 v9, 0xffff0000, v9
	v_and_b32_e32 v8, 0xffff0000, v8
	v_pk_fma_f32 v[6:7], v[16:17], v[10:11], v[6:7] op_sel_hi:[0,1,1]
	v_pk_fma_f32 v[2:3], v[16:17], v[8:9], v[2:3] op_sel_hi:[0,1,1]
	v_pk_fma_f32 v[12:13], v[16:17], v[20:21], v[12:13] op_sel_hi:[0,1,1]
	v_pk_fma_f32 v[6:7], v[18:19], v[6:7], v[10:11] op_sel_hi:[0,1,1] neg_lo:[0,0,1] neg_hi:[0,0,1]
	v_pk_fma_f32 v[2:3], v[18:19], v[2:3], v[8:9] op_sel_hi:[0,1,1] neg_lo:[0,0,1] neg_hi:[0,0,1]
	v_bfe_u32 v10, v1, 16, 1
	v_bfe_u32 v11, v0, 16, 1
	v_pk_fma_f32 v[12:13], v[18:19], v[12:13], v[20:21] op_sel_hi:[0,1,1] neg_lo:[0,0,1] neg_hi:[0,0,1]
	v_bfe_u32 v8, v3, 16, 1
	v_bfe_u32 v9, v2, 16, 1
	v_add3_u32 v0, v0, v11, s5
	v_add3_u32 v1, v1, v10, s5
	v_bfe_u32 v10, v6, 16, 1
	v_bfe_u32 v11, v7, 16, 1
	v_add3_u32 v2, v2, v9, s5
	v_add3_u32 v3, v3, v8, s5
	v_bfe_u32 v8, v12, 16, 1
	v_bfe_u32 v9, v13, 16, 1
	v_add3_u32 v7, v7, v11, s5
	v_add3_u32 v6, v6, v10, s5
	v_add3_u32 v9, v13, v9, s5
	v_add3_u32 v8, v12, v8, s5
	v_lshrrev_b32_e32 v6, 16, v6
	v_lshrrev_b32_e32 v7, 16, v7
	v_lshrrev_b32_e32 v8, 16, v8
	v_lshrrev_b32_e32 v9, 16, v9
	v_and_or_b32 v3, v3, s62, v7
	v_and_or_b32 v2, v2, s62, v6
	v_lshlrev_b64 v[6:7], 12, v[36:37]
	v_and_or_b32 v1, v1, s62, v9
	v_and_or_b32 v0, v0, s62, v8
	v_lshl_add_u64 v[4:5], v[4:5], 0, v[6:7]
	global_store_dwordx4 v[4:5], v[0:3], off
	s_nop 1
	s_branch .LBB0_601
